# MLA and SB block epilogues: DPP neighbour exchange instead of 64 serialized ds_bpermute round trips; early tile staging in MLA PV
# speedup vs baseline: 1.0083x; 1.0052x over previous
; __device__ __forceinline__ int crow(int r, int hi) { return (r & 3) + 8 * (r >> 2) + 4 * hi; }
; __device__ __forceinline__ void sb_block(const bf16* Qb, const bf16* Kh, const bf16* Vh, bf16* Ob, int q0, char* lds) {
;     ...
;     bf16* Ow = Ob + (size_t)(wid * QBLK) * SB_OS;
; #pragma unroll
;     for (int r = 0; r < 16; ++r) { const int orow = crow(r, hi);
; #pragma unroll
;         for (int d0 = 0; d0 < 4; ++d0) { const float v = o[d0][r];
;             const float vn = __shfl_xor(v, 1);
;             if ((r32 & 1) == 0) *(unsigned*)(Ow + (size_t)orow * SB_OS + d0 * 32 + r32) = cvtpk(v, vn); } }
.LBB0_703:
	s_lshl_b32 s4, s81, 5
	s_and_b32 s4, s4, 0xffffe000
	s_or_b32 s4, s4, s83
	s_ashr_i32 s5, s4, 31
	s_lshl_b64 s[4:5], s[4:5], 11
	s_add_u32 s4, s90, s4
	s_addc_u32 s5, s91, s5
	s_lshl_b32 s6, s88, 8
	s_and_b32 s6, s6, 0x700
	s_add_u32 s6, s4, s6
	s_addc_u32 s7, s5, 0
	s_ashr_i32 s93, s92, 31
	s_lshl_b64 s[4:5], s[92:93], 11
	s_add_u32 s6, s6, s4
	s_addc_u32 s7, s7, s5
	s_add_u32 s6, s6, 0x30000000
	s_addc_u32 s7, s7, 0
	v_lshlrev_b32_e32 v66, 1, v182
	v_lshl_add_u32 v66, v183, 13, v66
	v_mov_b32_e32 v88, v66
	v_add_u32_e32 v89, 0x1000, v66
	v_add_u32_e32 v90, 0x4000, v66
	v_add_u32_e32 v91, 0x5000, v66
	v_add_u32_e32 v92, 0x8000, v66
	v_add_u32_e32 v93, 0x9000, v66
	v_add_u32_e32 v94, 0xc000, v66
	v_add_u32_e32 v95, 0xd000, v66
	v_and_b32_e32 v0, 1, v181
	v_cmp_eq_u32_e64 s[4:5], 0, v0
	v_mov_b32_dpp v84, v2 quad_perm:[1,0,3,2] row_mask:0xf bank_mask:0xf
	v_cvt_pk_bf16_f32 v2, v2, v84
	v_mov_b32_dpp v85, v18 quad_perm:[1,0,3,2] row_mask:0xf bank_mask:0xf
	v_cvt_pk_bf16_f32 v18, v18, v85
	v_mov_b32_dpp v86, v34 quad_perm:[1,0,3,2] row_mask:0xf bank_mask:0xf
	v_cvt_pk_bf16_f32 v34, v34, v86
	v_mov_b32_dpp v87, v50 quad_perm:[1,0,3,2] row_mask:0xf bank_mask:0xf
	v_cvt_pk_bf16_f32 v50, v50, v87
	v_mov_b32_dpp v84, v3 quad_perm:[1,0,3,2] row_mask:0xf bank_mask:0xf
	v_cvt_pk_bf16_f32 v3, v3, v84
	v_mov_b32_dpp v85, v19 quad_perm:[1,0,3,2] row_mask:0xf bank_mask:0xf
	v_cvt_pk_bf16_f32 v19, v19, v85
	v_mov_b32_dpp v86, v35 quad_perm:[1,0,3,2] row_mask:0xf bank_mask:0xf
	v_cvt_pk_bf16_f32 v35, v35, v86
	v_mov_b32_dpp v87, v51 quad_perm:[1,0,3,2] row_mask:0xf bank_mask:0xf
	v_cvt_pk_bf16_f32 v51, v51, v87
	v_mov_b32_dpp v84, v4 quad_perm:[1,0,3,2] row_mask:0xf bank_mask:0xf
	v_cvt_pk_bf16_f32 v4, v4, v84
	v_mov_b32_dpp v85, v20 quad_perm:[1,0,3,2] row_mask:0xf bank_mask:0xf
	v_cvt_pk_bf16_f32 v20, v20, v85
	v_mov_b32_dpp v86, v36 quad_perm:[1,0,3,2] row_mask:0xf bank_mask:0xf
	v_cvt_pk_bf16_f32 v36, v36, v86
	v_mov_b32_dpp v87, v52 quad_perm:[1,0,3,2] row_mask:0xf bank_mask:0xf
	v_cvt_pk_bf16_f32 v52, v52, v87
	v_mov_b32_dpp v84, v5 quad_perm:[1,0,3,2] row_mask:0xf bank_mask:0xf
	v_cvt_pk_bf16_f32 v5, v5, v84
	v_mov_b32_dpp v85, v21 quad_perm:[1,0,3,2] row_mask:0xf bank_mask:0xf
	v_cvt_pk_bf16_f32 v21, v21, v85
	v_mov_b32_dpp v86, v37 quad_perm:[1,0,3,2] row_mask:0xf bank_mask:0xf
	v_cvt_pk_bf16_f32 v37, v37, v86
	v_mov_b32_dpp v87, v53 quad_perm:[1,0,3,2] row_mask:0xf bank_mask:0xf
	v_cvt_pk_bf16_f32 v53, v53, v87
	v_mov_b32_dpp v84, v6 quad_perm:[1,0,3,2] row_mask:0xf bank_mask:0xf
	v_cvt_pk_bf16_f32 v6, v6, v84
	v_mov_b32_dpp v85, v22 quad_perm:[1,0,3,2] row_mask:0xf bank_mask:0xf
	v_cvt_pk_bf16_f32 v22, v22, v85
	v_mov_b32_dpp v86, v38 quad_perm:[1,0,3,2] row_mask:0xf bank_mask:0xf
	v_cvt_pk_bf16_f32 v38, v38, v86
	v_mov_b32_dpp v87, v54 quad_perm:[1,0,3,2] row_mask:0xf bank_mask:0xf
	v_cvt_pk_bf16_f32 v54, v54, v87
	v_mov_b32_dpp v84, v7 quad_perm:[1,0,3,2] row_mask:0xf bank_mask:0xf
	v_cvt_pk_bf16_f32 v7, v7, v84
	v_mov_b32_dpp v85, v23 quad_perm:[1,0,3,2] row_mask:0xf bank_mask:0xf
	v_cvt_pk_bf16_f32 v23, v23, v85
	v_mov_b32_dpp v86, v39 quad_perm:[1,0,3,2] row_mask:0xf bank_mask:0xf
	v_cvt_pk_bf16_f32 v39, v39, v86
	v_mov_b32_dpp v87, v55 quad_perm:[1,0,3,2] row_mask:0xf bank_mask:0xf
	v_cvt_pk_bf16_f32 v55, v55, v87
	v_mov_b32_dpp v84, v8 quad_perm:[1,0,3,2] row_mask:0xf bank_mask:0xf
	v_cvt_pk_bf16_f32 v8, v8, v84
	v_mov_b32_dpp v85, v24 quad_perm:[1,0,3,2] row_mask:0xf bank_mask:0xf
	v_cvt_pk_bf16_f32 v24, v24, v85
	v_mov_b32_dpp v86, v40 quad_perm:[1,0,3,2] row_mask:0xf bank_mask:0xf
	v_cvt_pk_bf16_f32 v40, v40, v86
	v_mov_b32_dpp v87, v56 quad_perm:[1,0,3,2] row_mask:0xf bank_mask:0xf
	v_cvt_pk_bf16_f32 v56, v56, v87
	v_mov_b32_dpp v84, v9 quad_perm:[1,0,3,2] row_mask:0xf bank_mask:0xf
	v_cvt_pk_bf16_f32 v9, v9, v84
	v_mov_b32_dpp v85, v25 quad_perm:[1,0,3,2] row_mask:0xf bank_mask:0xf
	v_cvt_pk_bf16_f32 v25, v25, v85
	v_mov_b32_dpp v86, v41 quad_perm:[1,0,3,2] row_mask:0xf bank_mask:0xf
	v_cvt_pk_bf16_f32 v41, v41, v86
	v_mov_b32_dpp v87, v57 quad_perm:[1,0,3,2] row_mask:0xf bank_mask:0xf
	v_cvt_pk_bf16_f32 v57, v57, v87
	v_mov_b32_dpp v84, v10 quad_perm:[1,0,3,2] row_mask:0xf bank_mask:0xf
	v_cvt_pk_bf16_f32 v10, v10, v84
	v_mov_b32_dpp v85, v26 quad_perm:[1,0,3,2] row_mask:0xf bank_mask:0xf
	v_cvt_pk_bf16_f32 v26, v26, v85
	v_mov_b32_dpp v86, v42 quad_perm:[1,0,3,2] row_mask:0xf bank_mask:0xf
	v_cvt_pk_bf16_f32 v42, v42, v86
	v_mov_b32_dpp v87, v58 quad_perm:[1,0,3,2] row_mask:0xf bank_mask:0xf
	v_cvt_pk_bf16_f32 v58, v58, v87
	v_mov_b32_dpp v84, v11 quad_perm:[1,0,3,2] row_mask:0xf bank_mask:0xf
	v_cvt_pk_bf16_f32 v11, v11, v84
	v_mov_b32_dpp v85, v27 quad_perm:[1,0,3,2] row_mask:0xf bank_mask:0xf
	v_cvt_pk_bf16_f32 v27, v27, v85
	v_mov_b32_dpp v86, v43 quad_perm:[1,0,3,2] row_mask:0xf bank_mask:0xf
	v_cvt_pk_bf16_f32 v43, v43, v86
	v_mov_b32_dpp v87, v59 quad_perm:[1,0,3,2] row_mask:0xf bank_mask:0xf
	v_cvt_pk_bf16_f32 v59, v59, v87
	v_mov_b32_dpp v84, v12 quad_perm:[1,0,3,2] row_mask:0xf bank_mask:0xf
	v_cvt_pk_bf16_f32 v12, v12, v84
	v_mov_b32_dpp v85, v28 quad_perm:[1,0,3,2] row_mask:0xf bank_mask:0xf
	v_cvt_pk_bf16_f32 v28, v28, v85
	v_mov_b32_dpp v86, v44 quad_perm:[1,0,3,2] row_mask:0xf bank_mask:0xf
	v_cvt_pk_bf16_f32 v44, v44, v86
; __device__ __forceinline__ int crow(int r, int hi) { return (r & 3) + 8 * (r >> 2) + 4 * hi; }
; __device__ __forceinline__ void sb_block(const bf16* Qb, const bf16* Kh, const bf16* Vh, bf16* Ob, int q0, char* lds) {
;     ...
;     for (int r = 0; r < 16; ++r) { const int orow = crow(r, hi);
; #pragma unroll
;         for (int d0 = 0; d0 < 4; ++d0) { const float v = o[d0][r];
;             const float vn = __shfl_xor(v, 1);
;             if ((r32 & 1) == 0) *(unsigned*)(Ow + (size_t)orow * SB_OS + d0 * 32 + r32) = cvtpk(v, vn); } }
	v_mov_b32_dpp v87, v60 quad_perm:[1,0,3,2] row_mask:0xf bank_mask:0xf
	v_cvt_pk_bf16_f32 v60, v60, v87
	v_mov_b32_dpp v84, v13 quad_perm:[1,0,3,2] row_mask:0xf bank_mask:0xf
	v_cvt_pk_bf16_f32 v13, v13, v84
	v_mov_b32_dpp v85, v29 quad_perm:[1,0,3,2] row_mask:0xf bank_mask:0xf
	v_cvt_pk_bf16_f32 v29, v29, v85
	v_mov_b32_dpp v86, v45 quad_perm:[1,0,3,2] row_mask:0xf bank_mask:0xf
	v_cvt_pk_bf16_f32 v45, v45, v86
	v_mov_b32_dpp v87, v61 quad_perm:[1,0,3,2] row_mask:0xf bank_mask:0xf
	v_cvt_pk_bf16_f32 v61, v61, v87
	v_mov_b32_dpp v84, v14 quad_perm:[1,0,3,2] row_mask:0xf bank_mask:0xf
	v_cvt_pk_bf16_f32 v14, v14, v84
	v_mov_b32_dpp v85, v30 quad_perm:[1,0,3,2] row_mask:0xf bank_mask:0xf
	v_cvt_pk_bf16_f32 v30, v30, v85
	v_mov_b32_dpp v86, v46 quad_perm:[1,0,3,2] row_mask:0xf bank_mask:0xf
	v_cvt_pk_bf16_f32 v46, v46, v86
	v_mov_b32_dpp v87, v62 quad_perm:[1,0,3,2] row_mask:0xf bank_mask:0xf
	v_cvt_pk_bf16_f32 v62, v62, v87
	v_mov_b32_dpp v84, v15 quad_perm:[1,0,3,2] row_mask:0xf bank_mask:0xf
	v_cvt_pk_bf16_f32 v15, v15, v84
	v_mov_b32_dpp v85, v31 quad_perm:[1,0,3,2] row_mask:0xf bank_mask:0xf
	v_cvt_pk_bf16_f32 v31, v31, v85
	v_mov_b32_dpp v86, v47 quad_perm:[1,0,3,2] row_mask:0xf bank_mask:0xf
	v_cvt_pk_bf16_f32 v47, v47, v86
	v_mov_b32_dpp v87, v63 quad_perm:[1,0,3,2] row_mask:0xf bank_mask:0xf
	v_cvt_pk_bf16_f32 v63, v63, v87
	v_mov_b32_dpp v84, v16 quad_perm:[1,0,3,2] row_mask:0xf bank_mask:0xf
	v_cvt_pk_bf16_f32 v16, v16, v84
	v_mov_b32_dpp v85, v32 quad_perm:[1,0,3,2] row_mask:0xf bank_mask:0xf
	v_cvt_pk_bf16_f32 v32, v32, v85
	v_mov_b32_dpp v86, v48 quad_perm:[1,0,3,2] row_mask:0xf bank_mask:0xf
	v_cvt_pk_bf16_f32 v48, v48, v86
	v_mov_b32_dpp v87, v64 quad_perm:[1,0,3,2] row_mask:0xf bank_mask:0xf
	v_cvt_pk_bf16_f32 v64, v64, v87
	v_mov_b32_dpp v84, v17 quad_perm:[1,0,3,2] row_mask:0xf bank_mask:0xf
	v_cvt_pk_bf16_f32 v17, v17, v84
	v_mov_b32_dpp v85, v33 quad_perm:[1,0,3,2] row_mask:0xf bank_mask:0xf
	v_cvt_pk_bf16_f32 v33, v33, v85
	v_mov_b32_dpp v86, v49 quad_perm:[1,0,3,2] row_mask:0xf bank_mask:0xf
	v_cvt_pk_bf16_f32 v49, v49, v86
	v_mov_b32_dpp v87, v65 quad_perm:[1,0,3,2] row_mask:0xf bank_mask:0xf
	v_cvt_pk_bf16_f32 v65, v65, v87
	s_mov_b64 exec, s[4:5]
	global_store_dword v88, v2, s[6:7]
	global_store_dword v88, v18, s[6:7] offset:64
	global_store_dword v88, v34, s[6:7] offset:128
	global_store_dword v88, v50, s[6:7] offset:192
	global_store_dword v88, v3, s[6:7] offset:2048
	global_store_dword v88, v19, s[6:7] offset:2112
	global_store_dword v88, v35, s[6:7] offset:2176
	global_store_dword v88, v51, s[6:7] offset:2240
	global_store_dword v89, v4, s[6:7]
	global_store_dword v89, v20, s[6:7] offset:64
	global_store_dword v89, v36, s[6:7] offset:128
	global_store_dword v89, v52, s[6:7] offset:192
	global_store_dword v89, v5, s[6:7] offset:2048
	global_store_dword v89, v21, s[6:7] offset:2112
	global_store_dword v89, v37, s[6:7] offset:2176
	global_store_dword v89, v53, s[6:7] offset:2240
	global_store_dword v90, v6, s[6:7]
	global_store_dword v90, v22, s[6:7] offset:64
	global_store_dword v90, v38, s[6:7] offset:128
	global_store_dword v90, v54, s[6:7] offset:192
	global_store_dword v90, v7, s[6:7] offset:2048
	global_store_dword v90, v23, s[6:7] offset:2112
	global_store_dword v90, v39, s[6:7] offset:2176
	global_store_dword v90, v55, s[6:7] offset:2240
	global_store_dword v91, v8, s[6:7]
	global_store_dword v91, v24, s[6:7] offset:64
	global_store_dword v91, v40, s[6:7] offset:128
	global_store_dword v91, v56, s[6:7] offset:192
	global_store_dword v91, v9, s[6:7] offset:2048
	global_store_dword v91, v25, s[6:7] offset:2112
	global_store_dword v91, v41, s[6:7] offset:2176
	global_store_dword v91, v57, s[6:7] offset:2240
	global_store_dword v92, v10, s[6:7]
	global_store_dword v92, v26, s[6:7] offset:64
	global_store_dword v92, v42, s[6:7] offset:128
	global_store_dword v92, v58, s[6:7] offset:192
	global_store_dword v92, v11, s[6:7] offset:2048
	global_store_dword v92, v27, s[6:7] offset:2112
	global_store_dword v92, v43, s[6:7] offset:2176
	global_store_dword v92, v59, s[6:7] offset:2240
	global_store_dword v93, v12, s[6:7]
	global_store_dword v93, v28, s[6:7] offset:64
	global_store_dword v93, v44, s[6:7] offset:128
	global_store_dword v93, v60, s[6:7] offset:192
	global_store_dword v93, v13, s[6:7] offset:2048
	global_store_dword v93, v29, s[6:7] offset:2112
	global_store_dword v93, v45, s[6:7] offset:2176
	global_store_dword v93, v61, s[6:7] offset:2240
	global_store_dword v94, v14, s[6:7]
	global_store_dword v94, v30, s[6:7] offset:64
	global_store_dword v94, v46, s[6:7] offset:128
	global_store_dword v94, v62, s[6:7] offset:192
	global_store_dword v94, v15, s[6:7] offset:2048
	global_store_dword v94, v31, s[6:7] offset:2112
	global_store_dword v94, v47, s[6:7] offset:2176
	global_store_dword v94, v63, s[6:7] offset:2240
	global_store_dword v95, v16, s[6:7]
	global_store_dword v95, v32, s[6:7] offset:64
	global_store_dword v95, v48, s[6:7] offset:128
	global_store_dword v95, v64, s[6:7] offset:192
	global_store_dword v95, v17, s[6:7] offset:2048
	global_store_dword v95, v33, s[6:7] offset:2112
	global_store_dword v95, v49, s[6:7] offset:2176
	global_store_dword v95, v65, s[6:7] offset:2240
	s_nop 0
	s_mov_b64 s[6:7], -1
	s_branch .LBB0_684
